# diff attention loop: additionally 12 of the softmax exps per two tiles moved into the PV MFMA block (destinations that are free there), rescale-path temp renamed
# speedup vs baseline: 1.0072x; 1.0012x over previous
; template <int D0> __device__ __forceinline__ void pv_one(f32x16& od, int vb, bf16x8 pa0, bf16x8 pa1, bf16x8 pa2, bf16x8 pa3) {
;     const s16x4 l0 = tr_read<v_rd_off(D0, 0, 0)>(vb), h0 = tr_read<v_rd_off(D0, 0, 1)>(vb), l1 = tr_read<v_rd_off(D0, 1, 0)>(vb), h1 = tr_read<v_rd_off(D0, 1, 1)>(vb);
;     const s16x4 l2 = tr_read<v_rd_off(D0, 2, 0)>(vb), h2 = tr_read<v_rd_off(D0, 2, 1)>(vb), l3 = tr_read<v_rd_off(D0, 3, 0)>(vb), h3 = tr_read<v_rd_off(D0, 3, 1)>(vb);
;     asm volatile("s_waitcnt lgkmcnt(0)" ::: "memory"); SBAR();
;     ...
;     od = __builtin_amdgcn_mfma_f32_32x32x16_bf16(pa0, PK(l0, h0), od, 0, 0, 0);
;     od = __builtin_amdgcn_mfma_f32_32x32x16_bf16(pa1, PK(l1, h1), od, 0, 0, 0);
;     od = __builtin_amdgcn_mfma_f32_32x32x16_bf16(pa2, PK(l2, h2), od, 0, 0, 0);
;     od = __builtin_amdgcn_mfma_f32_32x32x16_bf16(pa3, PK(l3, h3), od, 0, 0, 0);
;     ...
; }
; __device__ __forceinline__ void pv_d0(f32x16* o, int vb, bf16x8 pa0, bf16x8 pa1, bf16x8 pa2, bf16x8 pa3) {
;     pv_one<0>(o[0], vb, pa0, pa1, pa2, pa3); pv_one<1>(o[1], vb, pa0, pa1, pa2, pa3); pv_one<2>(o[2], vb, pa0, pa1, pa2, pa3); pv_one<3>(o[3], vb, pa0, pa1, pa2, pa3);
; }
; __device__ __forceinline__ void partialSM(f32x16& p0, f32x16& p1, float& m_reg, float& mn, float& alpha, const float C, const float thr) {
;     float pmax = p0[0];
; #pragma unroll
;     for (int r = 1; r < 16; ++r) pmax = fmaxf(pmax, p0[r]);
; #pragma unroll
;     for (int r = 0; r < 16; ++r) pmax = fmaxf(pmax, p1[r]);
;     { auto rr = __builtin_amdgcn_permlane32_swap(__float_as_uint(pmax), __float_as_uint(pmax), false, false);
;       pmax = fmaxf(__uint_as_float(rr[0]), __uint_as_float(rr[1])); }
;     if (__builtin_expect(__all(pmax - m_reg <= thr), 1)) { mn = m_reg; alpha = 1.f; }
;     else { mn = fmaxf(m_reg, pmax); alpha = __builtin_amdgcn_exp2f((m_reg - mn) * C); m_reg = mn; }
;     const float mnC = -mn * C;
; #pragma unroll
;     for (int r = 0; r < 16; ++r) p0[r] = fmaf(p0[r], C, mnC);
; #pragma unroll
;     for (int r = 0; r < 16; ++r) p1[r] = fmaf(p1[r], C, mnC);
; #pragma unroll
;     for (int r = 0; r < 16; ++r) p0[r] = __builtin_amdgcn_exp2f(p0[r]);
; }
; __device__ __forceinline__ void finishSM(f32x16& p0, f32x16& p1, float alpha, float& l_reg, bf16x8& pa0, bf16x8& pa1, bf16x8& pa2, bf16x8& pa3) {
; #pragma unroll
;     for (int r = 0; r < 16; ++r) p1[r] = __builtin_amdgcn_exp2f(p1[r]);
;     float ps = 0;
.LBB0_171:
	s_add_i32 s37, s52, -3
	ds_read_b128 v[64:67], v186 offset:40960
	ds_read_b128 v[68:71], v186 offset:45056
	v_exp_f32_e32 v143, v138
	v_add_f32_e32 v138, 0, v217
	v_add_f32_e32 v138, v219, v138
	s_waitcnt lgkmcnt(1)
	v_mfma_f32_32x32x16_bf16 v[80:95], v[64:67], v[110:113], 0
	v_add_f32_e32 v138, v208, v138
	v_add_f32_e32 v138, v218, v138
	v_add_f32_e32 v138, v153, v138
	ds_read_b128 v[204:207], v188 offset:40960
	ds_read_b128 v[220:223], v188 offset:45056
	v_add_f32_e32 v138, v216, v138
	v_add_f32_e32 v138, v152, v138
	v_add_f32_e32 v138, v202, v138
	s_waitcnt lgkmcnt(2)
	v_mfma_f32_32x32x16_bf16 v[64:79], v[68:71], v[110:113], 0
	v_add_f32_e32 v138, v149, v138
	v_add_f32_e32 v138, v151, v138
	v_add_f32_e32 v138, v147, v138
	v_add_f32_e32 v138, v150, v138
	v_add_f32_e32 v138, v145, v138
	v_exp_f32_e32 v191, v139
	v_add_f32_e32 v138, v148, v138
	s_waitcnt lgkmcnt(1)
	v_mfma_f32_32x32x16_bf16 v[80:95], v[204:207], v[106:109], v[80:95]
	v_exp_f32_e32 v136, v136
	v_add_f32_e32 v138, v144, v138
	v_exp_f32_e32 v137, v137
	v_add_f32_e32 v138, v146, v138
	v_exp_f32_e32 v130, v130
	v_add_f32_e32 v138, v143, v138
	v_exp_f32_e32 v131, v131
	s_waitcnt lgkmcnt(0)
	v_mfma_f32_32x32x16_bf16 v[64:79], v[220:223], v[106:109], v[64:79]
	ds_read_b128 v[204:207], v190 offset:40960
	ds_read_b128 v[220:223], v190 offset:45056
	v_add_f32_e32 v138, v191, v138
	v_exp_f32_e32 v128, v128
	v_add_f32_e32 v138, v136, v138
	v_exp_f32_e32 v129, v129
	v_add_f32_e32 v138, v137, v138
	v_exp_f32_e32 v126, v126
	s_waitcnt lgkmcnt(1)
	v_mfma_f32_32x32x16_bf16 v[80:95], v[204:207], v[102:105], v[80:95]
	v_add_f32_e32 v138, v130, v138
	v_exp_f32_e32 v127, v127
	v_add_f32_e32 v138, v131, v138
	v_exp_f32_e32 v200, v140
	v_add_f32_e32 v138, v128, v138
	v_exp_f32_e32 v210, v141
	v_add_f32_e32 v138, v129, v138
	s_waitcnt lgkmcnt(0)
	v_mfma_f32_32x32x16_bf16 v[64:79], v[220:223], v[102:105], v[64:79]
	ds_read_b128 v[204:207], v192 offset:40960
	ds_read_b128 v[220:223], v192 offset:45056
	v_exp_f32_e32 v134, v134
	v_add_f32_e32 v138, v126, v138
	v_exp_f32_e32 v135, v135
	v_add_f32_e32 v138, v127, v138
	v_exp_f32_e32 v132, v132
	v_add_f32_e32 v138, v200, v138
	s_waitcnt lgkmcnt(1)
	v_mfma_f32_32x32x16_bf16 v[80:95], v[204:207], v[98:101], v[80:95]
	v_exp_f32_e32 v133, v133
	v_add_f32_e32 v138, v210, v138
	v_add_f32_e32 v138, v134, v138
	v_add_f32_e32 v138, v135, v138
	v_add_f32_e32 v138, v132, v138
	v_add_f32_e32 v196, v133, v138
	v_mov_b32_e32 v198, v196
	s_waitcnt lgkmcnt(0)
	v_mfma_f32_32x32x16_bf16 v[64:79], v[220:223], v[98:101], v[64:79]
	v_cvt_pk_bf16_f32 v138, v217, v219
	v_cvt_pk_bf16_f32 v139, v208, v218
	v_cvt_pk_bf16_f32 v140, v153, v216
	v_permlane32_swap_b32_e32 v196, v198
	v_cvt_pk_bf16_f32 v141, v152, v202
	v_permlane32_swap_b32_e32 v138, v140
	v_cvt_pk_bf16_f32 v204, v149, v151
	v_cvt_pk_bf16_f32 v205, v147, v150
	v_cvt_pk_bf16_f32 v206, v145, v148
	v_cvt_pk_bf16_f32 v207, v144, v146
	v_cvt_pk_bf16_f32 v144, v143, v191
	v_cvt_pk_bf16_f32 v145, v136, v137
	v_cvt_pk_bf16_f32 v146, v130, v131
	v_cvt_pk_bf16_f32 v147, v128, v129
	v_cvt_pk_bf16_f32 v148, v126, v127
	v_cvt_pk_bf16_f32 v149, v200, v210
	v_cvt_pk_bf16_f32 v150, v134, v135
	v_cvt_pk_bf16_f32 v151, v132, v133
	v_permlane32_swap_b32_e32 v139, v141
	v_permlane32_swap_b32_e32 v204, v206
	v_permlane32_swap_b32_e32 v205, v207
	v_permlane32_swap_b32_e32 v144, v146
	v_permlane32_swap_b32_e32 v145, v147
	v_permlane32_swap_b32_e32 v148, v150
	v_permlane32_swap_b32_e32 v149, v151
	s_cmp_lt_u32 s37, 30
	s_cselect_b32 s14, 0, 0xffffffe0
	s_cselect_b32 s15, s18, s86
	s_add_i32 s14, s14, s52
	s_lshl_b32 s14, s14, 6
	s_add_i32 s14, s14, s15
	s_sub_i32 s14, s14, 64
	s_ashr_i32 s15, s14, 31
	v_lshl_add_u64 v[126:127], s[14:15], 0, v[164:165]
	v_lshl_add_u64 v[130:131], v[168:169], 0, s[14:15]
	v_mad_u64_u32 v[128:129], s[38:39], v126, s9, v[170:171]
	v_mad_u64_u32 v[132:133], s[38:39], v130, s9, v[170:171]
	v_mad_i32_i24 v129, v127, s9, v129
	v_mad_i32_i24 v133, v131, s9, v133
	v_mad_i64_i32 v[134:135], s[14:15], s14, v195, v[166:167]
	global_load_dwordx4 v[126:129], v[128:129], off
	s_nop 0
	global_load_dwordx4 v[130:133], v[132:133], off
	s_nop 0
	global_load_dwordx4 v[134:137], v[134:135], off
	ds_read_b64_tr_b16 v[216:217], v180 offset:0
	ds_read_b64_tr_b16 v[218:219], v180 offset:0x800
	ds_read_b64_tr_b16 v[220:221], v180 offset:0x1000
	ds_read_b64_tr_b16 v[222:223], v180 offset:0x1800
	ds_read_b64_tr_b16 v[224:225], v180 offset:0x2000
	ds_read_b64_tr_b16 v[226:227], v180 offset:0x2800
	ds_read_b64_tr_b16 v[228:229], v180 offset:0x3000
	ds_read_b64_tr_b16 v[230:231], v180 offset:0x3800
	s_waitcnt lgkmcnt(0)
	s_nop 0
	v_mfma_f32_32x32x16_bf16 v[48:63], v[138:141], v[216:219], v[48:63]
	ds_read_b64_tr_b16 v[216:217], v180 offset:0x200
	ds_read_b64_tr_b16 v[218:219], v180 offset:0xa00
	v_max_f32_e32 v238, v81, v81
	v_max_f32_e32 v239, v80, v80
	v_max_f32_e32 v238, v239, v238
	v_max3_f32 v238, v238, v82, v83
	v_max3_f32 v238, v238, v84, v85
	v_max3_f32 v238, v238, v86, v87
	v_mfma_f32_32x32x16_bf16 v[48:63], v[204:207], v[220:223], v[48:63]
	ds_read_b64_tr_b16 v[220:221], v180 offset:0x1200
	ds_read_b64_tr_b16 v[222:223], v180 offset:0x1a00
	v_max3_f32 v238, v238, v88, v89
	v_max3_f32 v238, v238, v90, v91
	v_max3_f32 v238, v238, v92, v93
	v_max3_f32 v238, v238, v94, v95
	v_max3_f32 v238, v238, v64, v65
	v_max3_f32 v238, v238, v66, v67
	v_mfma_f32_32x32x16_bf16 v[48:63], v[144:147], v[224:227], v[48:63]
	ds_read_b64_tr_b16 v[224:225], v180 offset:0x2200
	ds_read_b64_tr_b16 v[226:227], v180 offset:0x2a00
	v_max3_f32 v238, v238, v68, v69
	v_max3_f32 v238, v238, v70, v71
	v_max3_f32 v238, v238, v72, v73
	v_max3_f32 v238, v238, v74, v75
	v_max3_f32 v238, v238, v76, v77
	v_max3_f32 v238, v238, v78, v79
	v_mfma_f32_32x32x16_bf16 v[48:63], v[148:151], v[228:231], v[48:63]
	ds_read_b64_tr_b16 v[228:229], v180 offset:0x3200
	ds_read_b64_tr_b16 v[230:231], v180 offset:0x3a00
	v_mov_b32_e32 v239, v238
	s_nop 1
	v_permlane32_swap_b32_e32 v238, v239
	v_max_f32_e32 v239, v239, v239
	v_max_f32_e32 v238, v238, v238
	v_max_f32_e32 v238, v238, v239
	s_waitcnt lgkmcnt(0)
; #define SBAR() __builtin_amdgcn_sched_barrier(0)
; template <int OFF> __device__ __forceinline__ s16x4 tr_read(int vb) { s16x4 r; asm volatile("ds_read_b64_tr_b16 %0, %1 offset:%2" : "=&v"(r) : "v"(vb), "i"(OFF) : "memory"); return r; }
; template <int D0> __device__ __forceinline__ void pv_one(f32x16& od, int vb, bf16x8 pa0, bf16x8 pa1, bf16x8 pa2, bf16x8 pa3) {
;     const s16x4 l0 = tr_read<v_rd_off(D0, 0, 0)>(vb), h0 = tr_read<v_rd_off(D0, 0, 1)>(vb), l1 = tr_read<v_rd_off(D0, 1, 0)>(vb), h1 = tr_read<v_rd_off(D0, 1, 1)>(vb);
;     const s16x4 l2 = tr_read<v_rd_off(D0, 2, 0)>(vb), h2 = tr_read<v_rd_off(D0, 2, 1)>(vb), l3 = tr_read<v_rd_off(D0, 3, 0)>(vb), h3 = tr_read<v_rd_off(D0, 3, 1)>(vb);
;     asm volatile("s_waitcnt lgkmcnt(0)" ::: "memory"); SBAR();
;     ...
;     od = __builtin_amdgcn_mfma_f32_32x32x16_bf16(pa0, PK(l0, h0), od, 0, 0, 0);
;     od = __builtin_amdgcn_mfma_f32_32x32x16_bf16(pa1, PK(l1, h1), od, 0, 0, 0);
;     od = __builtin_amdgcn_mfma_f32_32x32x16_bf16(pa2, PK(l2, h2), od, 0, 0, 0);
;     od = __builtin_amdgcn_mfma_f32_32x32x16_bf16(pa3, PK(l3, h3), od, 0, 0, 0);
;     ...
; }
; __device__ __forceinline__ void pv_d0(f32x16* o, int vb, bf16x8 pa0, bf16x8 pa1, bf16x8 pa2, bf16x8 pa3) {
;     pv_one<0>(o[0], vb, pa0, pa1, pa2, pa3); pv_one<1>(o[1], vb, pa0, pa1, pa2, pa3); pv_one<2>(o[2], vb, pa0, pa1, pa2, pa3); pv_one<3>(o[3], vb, pa0, pa1, pa2, pa3);
; }
; __device__ __forceinline__ void partialSM(f32x16& p0, f32x16& p1, float& m_reg, float& mn, float& alpha, const float C, const float thr) {
;     float pmax = p0[0];
; #pragma unroll
;     for (int r = 1; r < 16; ++r) pmax = fmaxf(pmax, p0[r]);
; #pragma unroll
;     for (int r = 0; r < 16; ++r) pmax = fmaxf(pmax, p1[r]);
;     { auto rr = __builtin_amdgcn_permlane32_swap(__float_as_uint(pmax), __float_as_uint(pmax), false, false);
;       pmax = fmaxf(__uint_as_float(rr[0]), __uint_as_float(rr[1])); }
;     if (__builtin_expect(__all(pmax - m_reg <= thr), 1)) { mn = m_reg; alpha = 1.f; }
;     else { mn = fmaxf(m_reg, pmax); alpha = __builtin_amdgcn_exp2f((m_reg - mn) * C); m_reg = mn; }
;     const float mnC = -mn * C;
; #pragma unroll
;     for (int r = 0; r < 16; ++r) p0[r] = fmaf(p0[r], C, mnC);
; #pragma unroll
;     for (int r = 0; r < 16; ++r) p1[r] = fmaf(p1[r], C, mnC);
; #pragma unroll
;     for (int r = 0; r < 16; ++r) p0[r] = __builtin_amdgcn_exp2f(p0[r]);
; }
	v_mfma_f32_32x32x16_bf16 v[32:47], v[138:141], v[216:219], v[32:47]
	ds_read_b64_tr_b16 v[216:217], v180 offset:0x400
	ds_read_b64_tr_b16 v[218:219], v180 offset:0xc00
	v_sub_f32_e32 v239, v238, v142
	v_cmp_ge_f32_e32 vcc, s76, v239
	v_max_f32_e32 v239, v142, v142
	v_max_f32_e32 v238, v239, v238
	v_sub_f32_e32 v239, v142, v238
	v_mul_f32_e32 v239, 0x3e38aa3b, v239
	v_mfma_f32_32x32x16_bf16 v[32:47], v[204:207], v[220:223], v[32:47]
	ds_read_b64_tr_b16 v[220:221], v180 offset:0x1400
	ds_read_b64_tr_b16 v[222:223], v180 offset:0x1c00
	v_exp_f32_e32 v239, v239
	s_cmp_eq_u64 vcc, exec
	s_cselect_b64 s[14:15], -1, 0
	v_cndmask_b32_e64 v200, v239, 1.0, s[14:15]
	v_cmp_gt_f32_e32 vcc, 1.0, v200
	v_mfma_f32_32x32x16_bf16 v[32:47], v[144:147], v[224:227], v[32:47]
	ds_read_b64_tr_b16 v[224:225], v180 offset:0x2400
	ds_read_b64_tr_b16 v[226:227], v180 offset:0x2c00
	v_cndmask_b32_e64 v241, v238, v142, s[14:15]
	v_mul_f32_e32 v239, 0xbe38aa3b, v241
	v_fmamk_f32 v80, v80, 0x3e38aa3b, v239
	v_fmamk_f32 v81, v81, 0x3e38aa3b, v239
	v_mfma_f32_32x32x16_bf16 v[32:47], v[148:151], v[228:231], v[32:47]
	ds_read_b64_tr_b16 v[228:229], v180 offset:0x3400
	ds_read_b64_tr_b16 v[230:231], v180 offset:0x3c00
	v_fmamk_f32 v82, v82, 0x3e38aa3b, v239
	v_fmamk_f32 v83, v83, 0x3e38aa3b, v239
	v_fmamk_f32 v84, v84, 0x3e38aa3b, v239
	v_fmamk_f32 v85, v85, 0x3e38aa3b, v239
	s_waitcnt lgkmcnt(0)
	v_mfma_f32_32x32x16_bf16 v[16:31], v[138:141], v[216:219], v[16:31]
	ds_read_b64_tr_b16 v[216:217], v180 offset:0x600
	ds_read_b64_tr_b16 v[218:219], v180 offset:0xe00
	v_fmamk_f32 v86, v86, 0x3e38aa3b, v239
	v_fmamk_f32 v87, v87, 0x3e38aa3b, v239
	v_fmamk_f32 v88, v88, 0x3e38aa3b, v239
	v_fmamk_f32 v89, v89, 0x3e38aa3b, v239
	v_mfma_f32_32x32x16_bf16 v[16:31], v[204:207], v[220:223], v[16:31]
	ds_read_b64_tr_b16 v[220:221], v180 offset:0x1600
	ds_read_b64_tr_b16 v[222:223], v180 offset:0x1e00
	v_fmamk_f32 v90, v90, 0x3e38aa3b, v239
	v_fmamk_f32 v91, v91, 0x3e38aa3b, v239
	v_fmamk_f32 v92, v92, 0x3e38aa3b, v239
	v_fmamk_f32 v93, v93, 0x3e38aa3b, v239
	v_mfma_f32_32x32x16_bf16 v[16:31], v[144:147], v[224:227], v[16:31]
	ds_read_b64_tr_b16 v[224:225], v180 offset:0x2600
	ds_read_b64_tr_b16 v[226:227], v180 offset:0x2e00
	v_fmamk_f32 v94, v94, 0x3e38aa3b, v239
	v_fmamk_f32 v95, v95, 0x3e38aa3b, v239
	v_mfma_f32_32x32x16_bf16 v[16:31], v[148:151], v[228:231], v[16:31]
	ds_read_b64_tr_b16 v[228:229], v180 offset:0x3600
	ds_read_b64_tr_b16 v[230:231], v180 offset:0x3e00
	v_exp_f32_e32 v153, v81
	v_exp_f32_e32 v152, v83
	v_exp_f32_e32 v143, v90
	s_waitcnt lgkmcnt(0)
	v_mfma_f32_32x32x16_bf16 v[0:15], v[138:141], v[216:219], v[0:15]
	v_mfma_f32_32x32x16_bf16 v[0:15], v[204:207], v[220:223], v[0:15]
	v_exp_f32_e32 v138, v80
	v_mfma_f32_32x32x16_bf16 v[0:15], v[144:147], v[224:227], v[0:15]
	v_exp_f32_e32 v139, v82
	v_mfma_f32_32x32x16_bf16 v[0:15], v[148:151], v[228:231], v[0:15]
	v_exp_f32_e32 v140, v84
	v_exp_f32_e32 v141, v86
	s_barrier
	s_waitcnt vmcnt(5)
	ds_write_b128 v181, v[114:117]
	s_waitcnt vmcnt(4)
	ds_write_b128 v184, v[118:121]
	s_waitcnt vmcnt(3)
	ds_write_b128 v182, v[122:125] offset:32768
	s_cbranch_vccz .LBB0_175
	s_and_saveexec_b64 s[38:39], s[12:13]
	ds_write_b32 v177, v200 offset:49280
	s_or_b64 exec, exec, s[38:39]
	s_waitcnt lgkmcnt(0)
	v_add_u32_e32 v242, v161, v96
	ds_read_b128 v[144:147], v242 offset:49376
	ds_read_b128 v[148:151], v242 offset:49344
	ds_read_b128 v[204:207], v242 offset:49312
	ds_read_b128 v[216:219], v242 offset:49280
	s_waitcnt lgkmcnt(3)
	v_pk_mul_f32 v[60:61], v[60:61], v[144:145]
	s_waitcnt lgkmcnt(2)
	v_pk_mul_f32 v[56:57], v[56:57], v[148:149]
	s_waitcnt lgkmcnt(1)
	v_pk_mul_f32 v[52:53], v[52:53], v[204:205]
	v_pk_mul_f32 v[62:63], v[62:63], v[146:147]
	v_pk_mul_f32 v[58:59], v[58:59], v[150:151]
	v_pk_mul_f32 v[54:55], v[54:55], v[206:207]
	s_waitcnt lgkmcnt(0)
	v_pk_mul_f32 v[50:51], v[50:51], v[218:219]
	v_pk_mul_f32 v[48:49], v[48:49], v[216:217]
	v_pk_mul_f32 v[44:45], v[44:45], v[144:145]
	v_pk_mul_f32 v[40:41], v[40:41], v[148:149]
	v_pk_mul_f32 v[36:37], v[36:37], v[204:205]
	v_pk_mul_f32 v[46:47], v[46:47], v[146:147]
	v_pk_mul_f32 v[42:43], v[42:43], v[150:151]
	v_pk_mul_f32 v[38:39], v[38:39], v[206:207]
	v_pk_mul_f32 v[34:35], v[34:35], v[218:219]
	v_pk_mul_f32 v[32:33], v[32:33], v[216:217]
	v_pk_mul_f32 v[28:29], v[28:29], v[144:145]
	v_pk_mul_f32 v[24:25], v[24:25], v[148:149]
	v_pk_mul_f32 v[20:21], v[20:21], v[204:205]
	v_pk_mul_f32 v[30:31], v[30:31], v[146:147]
	v_pk_mul_f32 v[26:27], v[26:27], v[150:151]
	v_pk_mul_f32 v[22:23], v[22:23], v[206:207]
	v_pk_mul_f32 v[18:19], v[18:19], v[218:219]
	v_pk_mul_f32 v[16:17], v[16:17], v[216:217]
	v_pk_mul_f32 v[12:13], v[12:13], v[144:145]
	v_pk_mul_f32 v[8:9], v[8:9], v[148:149]
	v_pk_mul_f32 v[4:5], v[4:5], v[204:205]
	v_pk_mul_f32 v[14:15], v[14:15], v[146:147]
	v_pk_mul_f32 v[10:11], v[10:11], v[150:151]
	v_pk_mul_f32 v[6:7], v[6:7], v[206:207]
	v_pk_mul_f32 v[2:3], v[2:3], v[218:219]
	v_pk_mul_f32 v[0:1], v[0:1], v[216:217]
; __device__ __forceinline__ void partialSM(f32x16& p0, f32x16& p1, float& m_reg, float& mn, float& alpha, const float C, const float thr) {
;     ...
;     const float mnC = -mn * C;
; #pragma unroll
;     for (int r = 0; r < 16; ++r) p0[r] = fmaf(p0[r], C, mnC);
; #pragma unroll
;     for (int r = 0; r < 16; ++r) p1[r] = fmaf(p1[r], C, mnC);
; #pragma unroll
;     for (int r = 0; r < 16; ++r) p0[r] = __builtin_amdgcn_exp2f(p0[r]);
; }
; __device__ __forceinline__ void finishSM(f32x16& p0, f32x16& p1, float alpha, float& l_reg, bf16x8& pa0, bf16x8& pa1, bf16x8& pa2, bf16x8& pa3) {
; #pragma unroll
;     for (int r = 0; r < 16; ++r) p1[r] = __builtin_amdgcn_exp2f(p1[r]);
;     float ps = 0;
; #pragma unroll
;     for (int r = 0; r < 16; ++r) ps += p0[r];
; #pragma unroll
;     for (int r = 0; r < 16; ++r) ps += p1[r];
;     { auto rr = __builtin_amdgcn_permlane32_swap(__float_as_uint(ps), __float_as_uint(ps), false, false);
;       ps = __uint_as_float(rr[0]) + __uint_as_float(rr[1]); }
;     l_reg = l_reg * alpha + ps;
;     ...
;     PK4(p0, 0, pa0); PK4(p0, 8, pa1); PK4(p1, 0, pa2); PK4(p1, 8, pa3);
.LBB0_175:
	v_cndmask_b32_e64 v202, v238, v142, s[14:15]
	v_mul_f32_e32 v204, 0xbe38aa3b, v202
	v_exp_f32_e32 v151, v85
	v_exp_f32_e32 v150, v87
	v_exp_f32_e32 v142, v88
	v_exp_f32_e32 v149, v89
	v_exp_f32_e32 v148, v91
	v_exp_f32_e32 v144, v92
	v_exp_f32_e32 v147, v93
	v_exp_f32_e32 v145, v94
	v_exp_f32_e32 v146, v95
	v_fmamk_f32 v222, v64, 0x3e38aa3b, v204
	v_fmamk_f32 v223, v65, 0x3e38aa3b, v204
	v_fmamk_f32 v224, v66, 0x3e38aa3b, v204
	v_fmamk_f32 v225, v67, 0x3e38aa3b, v204
	v_fmamk_f32 v226, v68, 0x3e38aa3b, v204
	v_fmamk_f32 v208, v69, 0x3e38aa3b, v204
	v_fmamk_f32 v216, v70, 0x3e38aa3b, v204
	v_fmamk_f32 v217, v71, 0x3e38aa3b, v204
	v_fmamk_f32 v218, v72, 0x3e38aa3b, v204
	v_fmamk_f32 v219, v73, 0x3e38aa3b, v204
	v_fmamk_f32 v220, v74, 0x3e38aa3b, v204
	v_fmamk_f32 v221, v75, 0x3e38aa3b, v204
	v_fmamk_f32 v206, v76, 0x3e38aa3b, v204
	v_fmamk_f32 v227, v77, 0x3e38aa3b, v204
	v_fmamk_f32 v228, v78, 0x3e38aa3b, v204
	v_fmac_f32_e32 v204, 0x3e38aa3b, v79
	s_waitcnt lgkmcnt(0)
	s_barrier
	ds_read_b128 v[64:67], v186 offset:32768
	ds_read_b128 v[68:71], v186 offset:36864
	v_exp_f32_e32 v205, v223
	v_exp_f32_e32 v223, v204
	v_add_f32_e32 v204, 0, v138
	v_add_f32_e32 v204, v153, v204
	s_waitcnt lgkmcnt(1)
	v_mfma_f32_32x32x16_bf16 v[80:95], v[64:67], v[110:113], 0
	v_add_f32_e32 v204, v139, v204
	v_add_f32_e32 v204, v152, v204
	v_add_f32_e32 v204, v140, v204
	ds_read_b128 v[230:233], v188 offset:32768
	ds_read_b128 v[234:237], v188 offset:36864
	v_add_f32_e32 v204, v151, v204
	v_add_f32_e32 v204, v141, v204
	v_add_f32_e32 v204, v150, v204
	s_waitcnt lgkmcnt(2)
	v_mfma_f32_32x32x16_bf16 v[64:79], v[68:71], v[110:113], 0
	v_add_f32_e32 v204, v142, v204
	v_add_f32_e32 v204, v149, v204
	v_add_f32_e32 v204, v143, v204
	v_add_f32_e32 v204, v148, v204
	v_exp_f32_e32 v191, v222
	v_add_f32_e32 v204, v144, v204
	v_add_f32_e32 v204, v147, v204
	s_waitcnt lgkmcnt(1)
	v_mfma_f32_32x32x16_bf16 v[80:95], v[230:233], v[106:109], v[80:95]
	v_exp_f32_e32 v207, v224
	v_add_f32_e32 v204, v145, v204
	v_exp_f32_e32 v210, v225
	v_add_f32_e32 v204, v146, v204
	v_exp_f32_e32 v211, v226
	v_add_f32_e32 v204, v191, v204
	v_exp_f32_e32 v208, v208
	s_waitcnt lgkmcnt(0)
	v_mfma_f32_32x32x16_bf16 v[64:79], v[234:237], v[106:109], v[64:79]
	ds_read_b128 v[230:233], v190 offset:32768
	ds_read_b128 v[234:237], v190 offset:36864
	v_add_f32_e32 v204, v205, v204
	v_exp_f32_e32 v212, v216
	v_add_f32_e32 v204, v207, v204
	v_exp_f32_e32 v213, v217
	v_add_f32_e32 v204, v210, v204
	v_exp_f32_e32 v216, v218
	s_waitcnt lgkmcnt(1)
	v_mfma_f32_32x32x16_bf16 v[80:95], v[230:233], v[102:105], v[80:95]
	v_add_f32_e32 v204, v211, v204
	v_exp_f32_e32 v217, v219
	v_add_f32_e32 v204, v208, v204
	v_exp_f32_e32 v218, v220
	v_add_f32_e32 v204, v212, v204
	v_exp_f32_e32 v219, v221
	v_add_f32_e32 v204, v213, v204
	s_waitcnt lgkmcnt(0)
	v_mfma_f32_32x32x16_bf16 v[64:79], v[234:237], v[102:105], v[64:79]
	ds_read_b128 v[230:233], v192 offset:32768
	ds_read_b128 v[234:237], v192 offset:36864
	v_exp_f32_e32 v220, v206
	v_add_f32_e32 v204, v216, v204
	v_exp_f32_e32 v221, v227
	v_add_f32_e32 v204, v217, v204
	v_exp_f32_e32 v222, v228
	v_add_f32_e32 v204, v218, v204
	s_waitcnt lgkmcnt(1)
	v_mfma_f32_32x32x16_bf16 v[80:95], v[230:233], v[98:101], v[80:95]
	v_add_f32_e32 v204, v219, v204
	v_add_f32_e32 v204, v220, v204
	v_add_f32_e32 v204, v221, v204
	v_add_f32_e32 v204, v222, v204
	v_add_f32_e32 v204, v223, v204
	v_mov_b32_e32 v206, v204
	v_cvt_pk_bf16_f32 v138, v138, v153
	s_waitcnt lgkmcnt(0)
	v_mfma_f32_32x32x16_bf16 v[64:79], v[234:237], v[98:101], v[64:79]
	v_cvt_pk_bf16_f32 v139, v139, v152
	v_cvt_pk_bf16_f32 v140, v140, v151
	v_cvt_pk_bf16_f32 v141, v141, v150
	v_cvt_pk_bf16_f32 v142, v142, v149
	v_cvt_pk_bf16_f32 v143, v143, v148
	v_cvt_pk_bf16_f32 v144, v144, v147
	v_cvt_pk_bf16_f32 v145, v145, v146
	v_cvt_pk_bf16_f32 v146, v191, v205
	v_cvt_pk_bf16_f32 v147, v207, v210
	v_cvt_pk_bf16_f32 v148, v211, v208
	v_cvt_pk_bf16_f32 v149, v212, v213
	v_cvt_pk_bf16_f32 v150, v216, v217
	v_cvt_pk_bf16_f32 v151, v218, v219
	v_cvt_pk_bf16_f32 v152, v220, v221
	v_cvt_pk_bf16_f32 v153, v222, v223
	v_permlane32_swap_b32_e32 v204, v206
	v_permlane32_swap_b32_e32 v138, v140
	v_permlane32_swap_b32_e32 v139, v141
	v_permlane32_swap_b32_e32 v142, v144
	v_permlane32_swap_b32_e32 v143, v145
	v_permlane32_swap_b32_e32 v146, v148
	v_permlane32_swap_b32_e32 v147, v149
	v_permlane32_swap_b32_e32 v150, v152
	v_permlane32_swap_b32_e32 v151, v153
	s_cmp_gt_u32 s37, 32
	s_cbranch_scc1 .LBB0_177
	s_cmp_lt_u32 s37, 29
	s_cselect_b32 s14, 0, 0xffffffe0
	s_cselect_b32 s15, s18, s86
	s_add_i32 s14, s14, s52
	s_lshl_b32 s14, s14, 6
	s_add_i32 s14, s14, s15
	s_ashr_i32 s15, s14, 31
	v_lshl_add_u64 v[114:115], s[14:15], 0, v[164:165]
	v_lshl_add_u64 v[118:119], v[168:169], 0, s[14:15]
	v_mad_u64_u32 v[116:117], s[38:39], v114, s9, v[170:171]
	v_mad_u64_u32 v[120:121], s[38:39], v118, s9, v[170:171]
	v_mad_i32_i24 v117, v115, s9, v117
	v_mad_i32_i24 v121, v119, s9, v121
	v_mad_i64_i32 v[122:123], s[14:15], s14, v195, v[166:167]
	global_load_dwordx4 v[114:117], v[116:117], off
	s_nop 0
	global_load_dwordx4 v[118:121], v[120:121], off
	s_nop 0
	global_load_dwordx4 v[122:125], v[122:123], off
; #define SBAR() __builtin_amdgcn_sched_barrier(0)
; template <int OFF> __device__ __forceinline__ s16x4 tr_read(int vb) { s16x4 r; asm volatile("ds_read_b64_tr_b16 %0, %1 offset:%2" : "=&v"(r) : "v"(vb), "i"(OFF) : "memory"); return r; }
; template <int D0> __device__ __forceinline__ void pv_one(f32x16& od, int vb, bf16x8 pa0, bf16x8 pa1, bf16x8 pa2, bf16x8 pa3) {
;     const s16x4 l0 = tr_read<v_rd_off(D0, 0, 0)>(vb), h0 = tr_read<v_rd_off(D0, 0, 1)>(vb), l1 = tr_read<v_rd_off(D0, 1, 0)>(vb), h1 = tr_read<v_rd_off(D0, 1, 1)>(vb);
;     const s16x4 l2 = tr_read<v_rd_off(D0, 2, 0)>(vb), h2 = tr_read<v_rd_off(D0, 2, 1)>(vb), l3 = tr_read<v_rd_off(D0, 3, 0)>(vb), h3 = tr_read<v_rd_off(D0, 3, 1)>(vb);
;     asm volatile("s_waitcnt lgkmcnt(0)" ::: "memory"); SBAR();
;     ...
;     od = __builtin_amdgcn_mfma_f32_32x32x16_bf16(pa0, PK(l0, h0), od, 0, 0, 0);
;     od = __builtin_amdgcn_mfma_f32_32x32x16_bf16(pa1, PK(l1, h1), od, 0, 0, 0);
;     od = __builtin_amdgcn_mfma_f32_32x32x16_bf16(pa2, PK(l2, h2), od, 0, 0, 0);
;     od = __builtin_amdgcn_mfma_f32_32x32x16_bf16(pa3, PK(l3, h3), od, 0, 0, 0);
;     ...
; }
; __device__ __forceinline__ void pv_d0(f32x16* o, int vb, bf16x8 pa0, bf16x8 pa1, bf16x8 pa2, bf16x8 pa3) {
;     pv_one<0>(o[0], vb, pa0, pa1, pa2, pa3); pv_one<1>(o[1], vb, pa0, pa1, pa2, pa3); pv_one<2>(o[2], vb, pa0, pa1, pa2, pa3); pv_one<3>(o[3], vb, pa0, pa1, pa2, pa3);
; }
; __device__ __forceinline__ void partialSM(f32x16& p0, f32x16& p1, float& m_reg, float& mn, float& alpha, const float C, const float thr) {
;     float pmax = p0[0];
; #pragma unroll
;     for (int r = 1; r < 16; ++r) pmax = fmaxf(pmax, p0[r]);
; #pragma unroll
;     for (int r = 0; r < 16; ++r) pmax = fmaxf(pmax, p1[r]);
;     { auto rr = __builtin_amdgcn_permlane32_swap(__float_as_uint(pmax), __float_as_uint(pmax), false, false);
;       pmax = fmaxf(__uint_as_float(rr[0]), __uint_as_float(rr[1])); }
;     if (__builtin_expect(__all(pmax - m_reg <= thr), 1)) { mn = m_reg; alpha = 1.f; }
;     else { mn = fmaxf(m_reg, pmax); alpha = __builtin_amdgcn_exp2f((m_reg - mn) * C); m_reg = mn; }
;     const float mnC = -mn * C;
; #pragma unroll
;     for (int r = 0; r < 16; ++r) p0[r] = fmaf(p0[r], C, mnC);
; #pragma unroll
;     for (int r = 0; r < 16; ++r) p1[r] = fmaf(p1[r], C, mnC);
; #pragma unroll
;     for (int r = 0; r < 16; ++r) p0[r] = __builtin_amdgcn_exp2f(p0[r]);
; }
.LBB0_177:
	ds_read_b64_tr_b16 v[216:217], v179 offset:0
	ds_read_b64_tr_b16 v[218:219], v179 offset:0x800
	ds_read_b64_tr_b16 v[220:221], v179 offset:0x1000
	ds_read_b64_tr_b16 v[222:223], v179 offset:0x1800
	ds_read_b64_tr_b16 v[224:225], v179 offset:0x2000
	ds_read_b64_tr_b16 v[226:227], v179 offset:0x2800
	ds_read_b64_tr_b16 v[228:229], v179 offset:0x3000
	ds_read_b64_tr_b16 v[230:231], v179 offset:0x3800
	s_waitcnt lgkmcnt(0)
	s_nop 0
	v_mfma_f32_32x32x16_bf16 v[48:63], v[138:141], v[216:219], v[48:63]
	ds_read_b64_tr_b16 v[216:217], v179 offset:0x200
	ds_read_b64_tr_b16 v[218:219], v179 offset:0xa00
	v_max_f32_e32 v238, v81, v81
	v_max_f32_e32 v239, v80, v80
	v_max_f32_e32 v238, v239, v238
	v_max3_f32 v238, v238, v82, v83
	v_max3_f32 v238, v238, v84, v85
	v_max3_f32 v238, v238, v86, v87
	v_mfma_f32_32x32x16_bf16 v[48:63], v[142:145], v[220:223], v[48:63]
	ds_read_b64_tr_b16 v[220:221], v179 offset:0x1200
	ds_read_b64_tr_b16 v[222:223], v179 offset:0x1a00
	v_max3_f32 v238, v238, v88, v89
	v_max3_f32 v238, v238, v90, v91
	v_max3_f32 v238, v238, v92, v93
	v_max3_f32 v238, v238, v94, v95
	v_max3_f32 v238, v238, v64, v65
	v_max3_f32 v238, v238, v66, v67
	v_mfma_f32_32x32x16_bf16 v[48:63], v[146:149], v[224:227], v[48:63]
	ds_read_b64_tr_b16 v[224:225], v179 offset:0x2200
	ds_read_b64_tr_b16 v[226:227], v179 offset:0x2a00
	v_max3_f32 v238, v238, v68, v69
	v_max3_f32 v238, v238, v70, v71
	v_max3_f32 v238, v238, v72, v73
	v_max3_f32 v238, v238, v74, v75
	v_max3_f32 v238, v238, v76, v77
	v_max3_f32 v238, v238, v78, v79
	v_mfma_f32_32x32x16_bf16 v[48:63], v[150:153], v[228:231], v[48:63]
	ds_read_b64_tr_b16 v[228:229], v179 offset:0x3200
	ds_read_b64_tr_b16 v[230:231], v179 offset:0x3a00
	v_mov_b32_e32 v239, v238
	s_nop 1
	v_permlane32_swap_b32_e32 v238, v239
	v_max_f32_e32 v239, v239, v239
	v_max_f32_e32 v238, v238, v238
	v_max_f32_e32 v238, v238, v239
	s_waitcnt lgkmcnt(0)
	v_mfma_f32_32x32x16_bf16 v[32:47], v[138:141], v[216:219], v[32:47]
	ds_read_b64_tr_b16 v[216:217], v179 offset:0x400
	ds_read_b64_tr_b16 v[218:219], v179 offset:0xc00
	v_sub_f32_e32 v239, v238, v202
	v_cmp_ge_f32_e32 vcc, s76, v239
	v_max_f32_e32 v239, v202, v202
	v_max_f32_e32 v238, v239, v238
	v_sub_f32_e32 v239, v202, v238
	v_mul_f32_e32 v239, 0x3e38aa3b, v239
	v_mfma_f32_32x32x16_bf16 v[32:47], v[142:145], v[220:223], v[32:47]
	ds_read_b64_tr_b16 v[220:221], v179 offset:0x1400
	ds_read_b64_tr_b16 v[222:223], v179 offset:0x1c00
	v_exp_f32_e32 v239, v239
	s_cmp_eq_u64 vcc, exec
	s_cselect_b64 s[14:15], -1, 0
	v_cndmask_b32_e64 v240, v239, 1.0, s[14:15]
	v_cmp_gt_f32_e32 vcc, 1.0, v240
	v_mfma_f32_32x32x16_bf16 v[32:47], v[146:149], v[224:227], v[32:47]
	ds_read_b64_tr_b16 v[224:225], v179 offset:0x2400
	ds_read_b64_tr_b16 v[226:227], v179 offset:0x2c00
	v_cndmask_b32_e64 v241, v238, v202, s[14:15]
	v_mul_f32_e32 v239, 0xbe38aa3b, v241
	v_fmamk_f32 v80, v80, 0x3e38aa3b, v239
	v_fmamk_f32 v81, v81, 0x3e38aa3b, v239
	v_mfma_f32_32x32x16_bf16 v[32:47], v[150:153], v[228:231], v[32:47]
	ds_read_b64_tr_b16 v[228:229], v179 offset:0x3400
	ds_read_b64_tr_b16 v[230:231], v179 offset:0x3c00
	v_fmamk_f32 v82, v82, 0x3e38aa3b, v239
	v_fmamk_f32 v83, v83, 0x3e38aa3b, v239
	v_fmamk_f32 v84, v84, 0x3e38aa3b, v239
	v_fmamk_f32 v85, v85, 0x3e38aa3b, v239
	s_waitcnt lgkmcnt(0)
	v_mfma_f32_32x32x16_bf16 v[16:31], v[138:141], v[216:219], v[16:31]
	ds_read_b64_tr_b16 v[216:217], v179 offset:0x600
	ds_read_b64_tr_b16 v[218:219], v179 offset:0xe00
	v_fmamk_f32 v86, v86, 0x3e38aa3b, v239
	v_fmamk_f32 v87, v87, 0x3e38aa3b, v239
	v_fmamk_f32 v88, v88, 0x3e38aa3b, v239
	v_fmamk_f32 v89, v89, 0x3e38aa3b, v239
	v_mfma_f32_32x32x16_bf16 v[16:31], v[142:145], v[220:223], v[16:31]
	ds_read_b64_tr_b16 v[220:221], v179 offset:0x1600
	ds_read_b64_tr_b16 v[222:223], v179 offset:0x1e00
	v_fmamk_f32 v90, v90, 0x3e38aa3b, v239
	v_fmamk_f32 v91, v91, 0x3e38aa3b, v239
	v_fmamk_f32 v92, v92, 0x3e38aa3b, v239
	v_fmamk_f32 v93, v93, 0x3e38aa3b, v239
	v_mfma_f32_32x32x16_bf16 v[16:31], v[146:149], v[224:227], v[16:31]
	ds_read_b64_tr_b16 v[224:225], v179 offset:0x2600
	ds_read_b64_tr_b16 v[226:227], v179 offset:0x2e00
	v_fmamk_f32 v94, v94, 0x3e38aa3b, v239
	v_mfma_f32_32x32x16_bf16 v[16:31], v[150:153], v[228:231], v[16:31]
	ds_read_b64_tr_b16 v[228:229], v179 offset:0x3600
	ds_read_b64_tr_b16 v[230:231], v179 offset:0x3e00
	v_exp_f32_e32 v208, v82
	s_waitcnt lgkmcnt(0)
	v_mfma_f32_32x32x16_bf16 v[0:15], v[138:141], v[216:219], v[0:15]
	v_mfma_f32_32x32x16_bf16 v[0:15], v[142:145], v[220:223], v[0:15]
	v_exp_f32_e32 v217, v80
	v_mfma_f32_32x32x16_bf16 v[0:15], v[146:149], v[224:227], v[0:15]
	v_exp_f32_e32 v219, v81
	v_mfma_f32_32x32x16_bf16 v[0:15], v[150:153], v[228:231], v[0:15]
	v_exp_f32_e32 v218, v83
	v_exp_f32_e32 v216, v85
	v_mov_b32_e32 v143, v240
	s_barrier
	s_waitcnt vmcnt(2)
	ds_write_b128 v181, v[126:129] offset:16384
	s_waitcnt vmcnt(1)
	ds_write_b128 v184, v[130:133] offset:16384
	s_waitcnt vmcnt(0)
	ds_write_b128 v182, v[134:137] offset:40960
	s_cbranch_vccz .LBB0_181
	s_and_saveexec_b64 s[38:39], s[12:13]
	ds_write_b32 v177, v143 offset:49280
	s_or_b64 exec, exec, s[38:39]
	s_waitcnt lgkmcnt(0)
	v_add_u32_e32 v139, v161, v96
	ds_read_b128 v[126:129], v139 offset:49376
	ds_read_b128 v[130:133], v139 offset:49344
	ds_read_b128 v[134:137], v139 offset:49312
	ds_read_b128 v[144:147], v139 offset:49280
	s_waitcnt lgkmcnt(3)
	v_pk_mul_f32 v[60:61], v[60:61], v[126:127]
	s_waitcnt lgkmcnt(2)
	v_pk_mul_f32 v[56:57], v[56:57], v[130:131]
	s_waitcnt lgkmcnt(1)
	v_pk_mul_f32 v[52:53], v[52:53], v[134:135]
	v_pk_mul_f32 v[62:63], v[62:63], v[128:129]
	v_pk_mul_f32 v[58:59], v[58:59], v[132:133]
	v_pk_mul_f32 v[54:55], v[54:55], v[136:137]
	s_waitcnt lgkmcnt(0)
	v_pk_mul_f32 v[50:51], v[50:51], v[146:147]
	v_pk_mul_f32 v[48:49], v[48:49], v[144:145]
	v_pk_mul_f32 v[44:45], v[44:45], v[126:127]
	v_pk_mul_f32 v[40:41], v[40:41], v[130:131]
	v_pk_mul_f32 v[36:37], v[36:37], v[134:135]
	v_pk_mul_f32 v[46:47], v[46:47], v[128:129]
	v_pk_mul_f32 v[42:43], v[42:43], v[132:133]
	v_pk_mul_f32 v[38:39], v[38:39], v[136:137]
	v_pk_mul_f32 v[34:35], v[34:35], v[146:147]
	v_pk_mul_f32 v[32:33], v[32:33], v[144:145]
	v_pk_mul_f32 v[28:29], v[28:29], v[126:127]
	v_pk_mul_f32 v[24:25], v[24:25], v[130:131]
	v_pk_mul_f32 v[20:21], v[20:21], v[134:135]
	v_pk_mul_f32 v[30:31], v[30:31], v[128:129]
	v_pk_mul_f32 v[26:27], v[26:27], v[132:133]
	v_pk_mul_f32 v[22:23], v[22:23], v[136:137]
	v_pk_mul_f32 v[18:19], v[18:19], v[146:147]
	v_pk_mul_f32 v[16:17], v[16:17], v[144:145]
	v_pk_mul_f32 v[12:13], v[12:13], v[126:127]
	v_pk_mul_f32 v[8:9], v[8:9], v[130:131]
	v_pk_mul_f32 v[4:5], v[4:5], v[134:135]
	v_pk_mul_f32 v[14:15], v[14:15], v[128:129]
	v_pk_mul_f32 v[10:11], v[10:11], v[132:133]
	v_pk_mul_f32 v[6:7], v[6:7], v[136:137]
	v_pk_mul_f32 v[2:3], v[2:3], v[146:147]
	v_pk_mul_f32 v[0:1], v[0:1], v[144:145]
; __device__ __forceinline__ void partialSM(f32x16& p0, f32x16& p1, float& m_reg, float& mn, float& alpha, const float C, const float thr) {
;     ...
;     const float mnC = -mn * C;
; #pragma unroll
;     for (int r = 0; r < 16; ++r) p0[r] = fmaf(p0[r], C, mnC);
; #pragma unroll
;     for (int r = 0; r < 16; ++r) p1[r] = fmaf(p1[r], C, mnC);
; #pragma unroll
;     for (int r = 0; r < 16; ++r) p0[r] = __builtin_amdgcn_exp2f(p0[r]);
; }
; __device__ __forceinline__ void finishSM(f32x16& p0, f32x16& p1, float alpha, float& l_reg, bf16x8& pa0, bf16x8& pa1, bf16x8& pa2, bf16x8& pa3) {
; #pragma unroll
;     for (int r = 0; r < 16; ++r) p1[r] = __builtin_amdgcn_exp2f(p1[r]);
;     float ps = 0;
; #pragma unroll
;     for (int r = 0; r < 16; ++r) ps += p0[r];
; #pragma unroll
;     for (int r = 0; r < 16; ++r) ps += p1[r];
;     { auto rr = __builtin_amdgcn_permlane32_swap(__float_as_uint(ps), __float_as_uint(ps), false, false);
;       ps = __uint_as_float(rr[0]) + __uint_as_float(rr[1]); }
;     l_reg = l_reg * alpha + ps;
.LBB0_181:
	v_cndmask_b32_e64 v142, v238, v202, s[14:15]
	v_mul_f32_e32 v132, 0xbe38aa3b, v142
	v_mov_b32_e32 v133, v132
	v_fmac_f32_e32 v133, 0x3e38aa3b, v95
	v_exp_f32_e32 v153, v84
	v_exp_f32_e32 v152, v86
	v_exp_f32_e32 v202, v87
	v_exp_f32_e32 v149, v88
	v_exp_f32_e32 v151, v89
	v_exp_f32_e32 v147, v90
	v_exp_f32_e32 v150, v91
	v_exp_f32_e32 v145, v92
	v_exp_f32_e32 v148, v93
	v_exp_f32_e32 v144, v94
	v_exp_f32_e32 v146, v133
	v_pk_fma_f32 v[138:139], v[64:65], s[8:9], v[132:133] op_sel_hi:[1,0,0]
	v_add_f32_e32 v64, v196, v198
	v_fmac_f32_e32 v64, v194, v178
	v_add_f32_e32 v178, v204, v206
	s_add_i32 s52, s52, 2
	v_pk_fma_f32 v[136:137], v[66:67], s[8:9], v[132:133] op_sel_hi:[1,0,0]
	v_pk_fma_f32 v[130:131], v[68:69], s[8:9], v[132:133] op_sel_hi:[1,0,0]
	v_pk_fma_f32 v[128:129], v[70:71], s[8:9], v[132:133] op_sel_hi:[1,0,0]
	v_pk_fma_f32 v[126:127], v[72:73], s[8:9], v[132:133] op_sel_hi:[1,0,0]
	v_pk_fma_f32 v[140:141], v[74:75], s[8:9], v[132:133] op_sel_hi:[1,0,0]
	v_pk_fma_f32 v[134:135], v[76:77], s[8:9], v[132:133] op_sel_hi:[1,0,0]
	v_pk_fma_f32 v[132:133], v[78:79], s[8:9], v[132:133] op_sel_hi:[1,0,0]
	v_fmac_f32_e32 v178, v64, v200
	s_cmp_gt_u32 s37, 32
	s_waitcnt lgkmcnt(0)
	s_barrier
	s_cbranch_scc1 .LBB0_183
	v_mov_b32_e32 v194, v143
	s_branch .LBB0_171
